# v70 + gate tiles (u8 sigmoid gates) stored with nt so they are not dirty in L2 at the pair barrier's writeback
# speedup vs baseline: 1.0083x; 1.0035x over previous
.LBB0_1363:
	s_and_b64 vcc, exec, s[4:5]
	s_cbranch_vccz .LBB0_1538
	v_mul_f32_e32 v128, 0xbfb8aa3b, v128
	v_exp_f32_e32 v128, v128
	v_mul_f32_e32 v129, 0xbfb8aa3b, v129
	v_exp_f32_e32 v129, v129
	v_mul_f32_e32 v130, 0xbfb8aa3b, v130
	v_exp_f32_e32 v130, v130
	v_add_f32_e32 v128, 1.0, v128
	v_rcp_f32_e32 v128, v128
	v_add_f32_e32 v129, 1.0, v129
	v_mul_f32_e32 v131, 0xbfb8aa3b, v131
	v_rcp_f32_e32 v129, v129
	v_add_f32_e32 v130, 1.0, v130
	v_exp_f32_e32 v131, v131
	v_rcp_f32_e32 v130, v130
	v_fma_f32 v128, v128, s29, -0.5
	v_cvt_pk_u8_f32 v128, v128, 0, 0
	v_fma_f32 v129, v129, s29, -0.5
	v_mul_f32_e32 v124, 0xbfb8aa3b, v124
	v_add_f32_e32 v131, 1.0, v131
	v_cvt_pk_u8_f32 v128, v129, 1, v128
	v_fma_f32 v129, v130, s29, -0.5
	v_exp_f32_e32 v130, v124
	v_mov_b32_e32 v124, v125
	v_rcp_f32_e32 v131, v131
	v_mul_f32_e32 v120, 0xbfb8aa3b, v120
	v_mul_f32_e32 v116, 0xbfb8aa3b, v116
	v_mul_f32_e32 v124, 0xbfb8aa3b, v124
	v_exp_f32_e32 v120, v120
	v_mul_f32_e32 v121, 0xbfb8aa3b, v121
	v_exp_f32_e32 v116, v116
	v_mul_f32_e32 v117, 0xbfb8aa3b, v117
	v_exp_f32_e32 v125, v124
	v_mul_f32_e32 v126, 0xbfb8aa3b, v126
	v_exp_f32_e32 v121, v121
	v_mul_f32_e32 v122, 0xbfb8aa3b, v122
	v_exp_f32_e32 v117, v117
	v_mul_f32_e32 v118, 0xbfb8aa3b, v118
	v_exp_f32_e32 v126, v126
	v_mul_f32_e32 v127, 0xbfb8aa3b, v127
	v_exp_f32_e32 v122, v122
	v_mul_f32_e32 v123, 0xbfb8aa3b, v123
	v_exp_f32_e32 v118, v118
	v_mul_f32_e32 v119, 0xbfb8aa3b, v119
	v_cvt_pk_u8_f32 v128, v129, 2, v128
	v_fma_f32 v129, v131, s29, -0.5
	v_exp_f32_e32 v127, v127
	v_exp_f32_e32 v123, v123
	v_exp_f32_e32 v119, v119
	v_cvt_pk_u8_f32 v124, v129, 3, v128
	v_add_f32_e32 v128, 1.0, v130
	v_add_f32_e32 v120, 1.0, v120
	v_add_f32_e32 v116, 1.0, v116
	v_rcp_f32_e32 v128, v128
	v_add_f32_e32 v125, 1.0, v125
	v_rcp_f32_e32 v120, v120
	v_add_f32_e32 v121, 1.0, v121
	v_rcp_f32_e32 v116, v116
	v_add_f32_e32 v117, 1.0, v117
	v_rcp_f32_e32 v125, v125
	v_add_f32_e32 v126, 1.0, v126
	v_rcp_f32_e32 v121, v121
	v_add_f32_e32 v122, 1.0, v122
	v_rcp_f32_e32 v117, v117
	v_add_f32_e32 v118, 1.0, v118
	v_rcp_f32_e32 v126, v126
	v_add_f32_e32 v127, 1.0, v127
	v_rcp_f32_e32 v122, v122
	v_add_f32_e32 v123, 1.0, v123
	v_rcp_f32_e32 v118, v118
	v_add_f32_e32 v119, 1.0, v119
	v_rcp_f32_e32 v127, v127
	v_rcp_f32_e32 v123, v123
	v_rcp_f32_e32 v119, v119
	s_add_i32 s67, s67, 0x7ffff500
	v_fma_f32 v128, v128, s29, -0.5
	v_fma_f32 v120, v120, s29, -0.5
	v_fma_f32 v116, v116, s29, -0.5
	s_and_b32 s4, s67, 0x7fffff00
	v_readlane_b32 s5, v255, 7
	v_cvt_pk_u8_f32 v128, v128, 0, 0
	v_fma_f32 v125, v125, s29, -0.5
	v_cvt_pk_u8_f32 v120, v120, 0, 0
	v_fma_f32 v121, v121, s29, -0.5
	v_cvt_pk_u8_f32 v116, v116, 0, 0
	v_fma_f32 v117, v117, s29, -0.5
	s_or_b32 s4, s4, s5
	v_cvt_pk_u8_f32 v125, v125, 1, v128
	v_fma_f32 v126, v126, s29, -0.5
	v_cvt_pk_u8_f32 v120, v121, 1, v120
	v_fma_f32 v121, v122, s29, -0.5
	v_cvt_pk_u8_f32 v116, v117, 1, v116
	v_fma_f32 v117, v118, s29, -0.5
	v_lshl_add_u32 v2, v226, 4, s4
	v_cvt_pk_u8_f32 v125, v126, 2, v125
	v_fma_f32 v126, v127, s29, -0.5
	v_cvt_pk_u8_f32 v120, v121, 2, v120
	v_fma_f32 v121, v123, s29, -0.5
	v_cvt_pk_u8_f32 v116, v117, 2, v116
	v_fma_f32 v117, v119, s29, -0.5
	s_movk_i32 s20, 0xc00
	v_cvt_pk_u8_f32 v125, v126, 3, v125
	v_cvt_pk_u8_f32 v126, v121, 3, v120
	v_cvt_pk_u8_f32 v127, v117, 3, v116
	v_mad_u64_u32 v[116:117], s[4:5], v225, s20, v[2:3]
	global_store_dwordx4 v116, v[124:127], s[72:73] nt
	v_mul_f32_e32 v112, 0xbfb8aa3b, v112
	v_exp_f32_e32 v112, v112
	v_mul_f32_e32 v113, 0xbfb8aa3b, v113
	v_exp_f32_e32 v113, v113
	v_mul_f32_e32 v114, 0xbfb8aa3b, v114
	v_exp_f32_e32 v114, v114
	v_add_f32_e32 v112, 1.0, v112
	v_rcp_f32_e32 v112, v112
	v_add_f32_e32 v113, 1.0, v113
	v_mul_f32_e32 v115, 0xbfb8aa3b, v115
	v_rcp_f32_e32 v113, v113
	v_add_f32_e32 v114, 1.0, v114
	v_exp_f32_e32 v115, v115
	v_rcp_f32_e32 v114, v114
	v_fma_f32 v112, v112, s29, -0.5
	v_cvt_pk_u8_f32 v112, v112, 0, 0
	v_fma_f32 v113, v113, s29, -0.5
	v_mul_f32_e32 v108, 0xbfb8aa3b, v108
	v_add_f32_e32 v115, 1.0, v115
	v_cvt_pk_u8_f32 v112, v113, 1, v112
	v_fma_f32 v113, v114, s29, -0.5
	v_exp_f32_e32 v114, v108
	v_mov_b32_e32 v108, v109
	v_rcp_f32_e32 v115, v115
	v_mul_f32_e32 v104, 0xbfb8aa3b, v104
	v_mul_f32_e32 v100, 0xbfb8aa3b, v100
	v_mul_f32_e32 v108, 0xbfb8aa3b, v108
	v_exp_f32_e32 v104, v104
	v_mul_f32_e32 v105, 0xbfb8aa3b, v105
	v_exp_f32_e32 v100, v100
	v_mul_f32_e32 v101, 0xbfb8aa3b, v101
	v_exp_f32_e32 v109, v108
	v_mul_f32_e32 v110, 0xbfb8aa3b, v110
	v_exp_f32_e32 v105, v105
	v_mul_f32_e32 v106, 0xbfb8aa3b, v106
	v_exp_f32_e32 v101, v101
	v_mul_f32_e32 v102, 0xbfb8aa3b, v102
	v_exp_f32_e32 v110, v110
	v_mul_f32_e32 v111, 0xbfb8aa3b, v111
	v_exp_f32_e32 v106, v106
	v_mul_f32_e32 v107, 0xbfb8aa3b, v107
	v_exp_f32_e32 v102, v102
	v_mul_f32_e32 v103, 0xbfb8aa3b, v103
	v_cvt_pk_u8_f32 v112, v113, 2, v112
	v_fma_f32 v113, v115, s29, -0.5
	v_exp_f32_e32 v111, v111
	v_exp_f32_e32 v107, v107
	v_exp_f32_e32 v103, v103
	v_cvt_pk_u8_f32 v108, v113, 3, v112
	v_add_f32_e32 v112, 1.0, v114
	v_add_f32_e32 v104, 1.0, v104
	v_add_f32_e32 v100, 1.0, v100
	v_rcp_f32_e32 v112, v112
	v_add_f32_e32 v109, 1.0, v109
	v_rcp_f32_e32 v104, v104
	v_add_f32_e32 v105, 1.0, v105
	v_rcp_f32_e32 v100, v100
	v_add_f32_e32 v101, 1.0, v101
	v_rcp_f32_e32 v109, v109
	v_add_f32_e32 v110, 1.0, v110
	v_rcp_f32_e32 v105, v105
	v_add_f32_e32 v106, 1.0, v106
	v_rcp_f32_e32 v101, v101
	v_add_f32_e32 v102, 1.0, v102
	v_rcp_f32_e32 v110, v110
	v_add_f32_e32 v111, 1.0, v111
	v_rcp_f32_e32 v106, v106
	v_add_f32_e32 v107, 1.0, v107
	v_rcp_f32_e32 v102, v102
	v_add_f32_e32 v103, 1.0, v103
	v_rcp_f32_e32 v111, v111
	v_rcp_f32_e32 v107, v107
	v_rcp_f32_e32 v103, v103
	v_fma_f32 v112, v112, s29, -0.5
	v_fma_f32 v104, v104, s29, -0.5
	v_fma_f32 v100, v100, s29, -0.5
	v_cvt_pk_u8_f32 v112, v112, 0, 0
	v_fma_f32 v109, v109, s29, -0.5
	v_cvt_pk_u8_f32 v104, v104, 0, 0
	v_fma_f32 v105, v105, s29, -0.5
	v_cvt_pk_u8_f32 v100, v100, 0, 0
	v_fma_f32 v101, v101, s29, -0.5
	v_cvt_pk_u8_f32 v109, v109, 1, v112
	v_fma_f32 v110, v110, s29, -0.5
	v_cvt_pk_u8_f32 v104, v105, 1, v104
	v_fma_f32 v105, v106, s29, -0.5
	v_cvt_pk_u8_f32 v100, v101, 1, v100
	v_fma_f32 v101, v102, s29, -0.5
	v_cvt_pk_u8_f32 v109, v110, 2, v109
	v_fma_f32 v110, v111, s29, -0.5
	v_cvt_pk_u8_f32 v104, v105, 2, v104
	v_fma_f32 v105, v107, s29, -0.5
	v_cvt_pk_u8_f32 v100, v101, 2, v100
	v_fma_f32 v101, v103, s29, -0.5
	v_cvt_pk_u8_f32 v109, v110, 3, v109
	v_cvt_pk_u8_f32 v110, v105, 3, v104
	v_cvt_pk_u8_f32 v111, v101, 3, v100
	v_mad_u64_u32 v[100:101], s[4:5], v224, s20, v[2:3]
	global_store_dwordx4 v100, v[108:111], s[72:73] nt
	v_mul_f32_e32 v96, 0xbfb8aa3b, v96
	v_exp_f32_e32 v96, v96
	v_mul_f32_e32 v97, 0xbfb8aa3b, v97
	v_exp_f32_e32 v97, v97
	v_mul_f32_e32 v98, 0xbfb8aa3b, v98
	v_exp_f32_e32 v98, v98
	v_add_f32_e32 v96, 1.0, v96
	v_rcp_f32_e32 v96, v96
	v_add_f32_e32 v97, 1.0, v97
	v_mul_f32_e32 v99, 0xbfb8aa3b, v99
	v_rcp_f32_e32 v97, v97
	v_add_f32_e32 v98, 1.0, v98
	v_exp_f32_e32 v99, v99
	v_rcp_f32_e32 v98, v98
	v_fma_f32 v96, v96, s29, -0.5
	v_cvt_pk_u8_f32 v96, v96, 0, 0
	v_fma_f32 v97, v97, s29, -0.5
	v_mul_f32_e32 v92, 0xbfb8aa3b, v92
	v_add_f32_e32 v99, 1.0, v99
	v_cvt_pk_u8_f32 v96, v97, 1, v96
	v_fma_f32 v97, v98, s29, -0.5
	v_exp_f32_e32 v98, v92
	v_mov_b32_e32 v92, v93
	v_rcp_f32_e32 v99, v99
	v_mul_f32_e32 v88, 0xbfb8aa3b, v88
	v_mul_f32_e32 v84, 0xbfb8aa3b, v84
	v_mul_f32_e32 v92, 0xbfb8aa3b, v92
	v_exp_f32_e32 v88, v88
	v_mul_f32_e32 v89, 0xbfb8aa3b, v89
	v_exp_f32_e32 v84, v84
	v_mul_f32_e32 v85, 0xbfb8aa3b, v85
	v_exp_f32_e32 v93, v92
	v_mul_f32_e32 v94, 0xbfb8aa3b, v94
	v_exp_f32_e32 v89, v89
	v_mul_f32_e32 v90, 0xbfb8aa3b, v90
	v_exp_f32_e32 v85, v85
	v_mul_f32_e32 v86, 0xbfb8aa3b, v86
	v_exp_f32_e32 v94, v94
	v_mul_f32_e32 v95, 0xbfb8aa3b, v95
	v_exp_f32_e32 v90, v90
	v_mul_f32_e32 v91, 0xbfb8aa3b, v91
	v_exp_f32_e32 v86, v86
	v_mul_f32_e32 v87, 0xbfb8aa3b, v87
	v_cvt_pk_u8_f32 v96, v97, 2, v96
	v_fma_f32 v97, v99, s29, -0.5
	v_exp_f32_e32 v95, v95
	v_exp_f32_e32 v91, v91
	v_exp_f32_e32 v87, v87
	v_cvt_pk_u8_f32 v92, v97, 3, v96
	v_add_f32_e32 v96, 1.0, v98
	v_add_f32_e32 v88, 1.0, v88
	v_add_f32_e32 v84, 1.0, v84
	v_rcp_f32_e32 v96, v96
	v_add_f32_e32 v93, 1.0, v93
	v_rcp_f32_e32 v88, v88
	v_add_f32_e32 v89, 1.0, v89
	v_rcp_f32_e32 v84, v84
	v_add_f32_e32 v85, 1.0, v85
	v_rcp_f32_e32 v93, v93
	v_add_f32_e32 v94, 1.0, v94
	v_rcp_f32_e32 v89, v89
	v_add_f32_e32 v90, 1.0, v90
	v_rcp_f32_e32 v85, v85
	v_add_f32_e32 v86, 1.0, v86
	v_rcp_f32_e32 v94, v94
	v_add_f32_e32 v95, 1.0, v95
	v_rcp_f32_e32 v90, v90
	v_add_f32_e32 v91, 1.0, v91
	v_rcp_f32_e32 v86, v86
	v_add_f32_e32 v87, 1.0, v87
	v_rcp_f32_e32 v95, v95
	v_rcp_f32_e32 v91, v91
	v_rcp_f32_e32 v87, v87
	v_fma_f32 v96, v96, s29, -0.5
	v_fma_f32 v88, v88, s29, -0.5
	v_fma_f32 v84, v84, s29, -0.5
	v_cvt_pk_u8_f32 v96, v96, 0, 0
	v_fma_f32 v93, v93, s29, -0.5
	v_cvt_pk_u8_f32 v88, v88, 0, 0
	v_fma_f32 v89, v89, s29, -0.5
	v_cvt_pk_u8_f32 v84, v84, 0, 0
	v_fma_f32 v85, v85, s29, -0.5
	v_cvt_pk_u8_f32 v93, v93, 1, v96
	v_fma_f32 v94, v94, s29, -0.5
	v_cvt_pk_u8_f32 v88, v89, 1, v88
	v_fma_f32 v89, v90, s29, -0.5
	v_cvt_pk_u8_f32 v84, v85, 1, v84
	v_fma_f32 v85, v86, s29, -0.5
	v_cvt_pk_u8_f32 v93, v94, 2, v93
	v_fma_f32 v94, v95, s29, -0.5
	v_cvt_pk_u8_f32 v88, v89, 2, v88
	v_fma_f32 v89, v91, s29, -0.5
	v_cvt_pk_u8_f32 v84, v85, 2, v84
	v_fma_f32 v85, v87, s29, -0.5
	v_cvt_pk_u8_f32 v93, v94, 3, v93
	v_cvt_pk_u8_f32 v94, v89, 3, v88
	v_cvt_pk_u8_f32 v95, v85, 3, v84
	v_mad_u64_u32 v[84:85], s[4:5], v223, s20, v[2:3]
	global_store_dwordx4 v84, v[92:95], s[72:73] nt
	v_mul_f32_e32 v80, 0xbfb8aa3b, v80
	v_exp_f32_e32 v80, v80
	v_mul_f32_e32 v81, 0xbfb8aa3b, v81
	v_exp_f32_e32 v81, v81
	v_mul_f32_e32 v82, 0xbfb8aa3b, v82
	v_exp_f32_e32 v82, v82
	v_add_f32_e32 v80, 1.0, v80
	v_rcp_f32_e32 v80, v80
	v_add_f32_e32 v81, 1.0, v81
	v_mul_f32_e32 v83, 0xbfb8aa3b, v83
	v_rcp_f32_e32 v81, v81
	v_add_f32_e32 v82, 1.0, v82
	v_exp_f32_e32 v83, v83
	v_rcp_f32_e32 v82, v82
	v_fma_f32 v80, v80, s29, -0.5
	v_cvt_pk_u8_f32 v80, v80, 0, 0
	v_fma_f32 v81, v81, s29, -0.5
	v_mul_f32_e32 v76, 0xbfb8aa3b, v76
	v_add_f32_e32 v83, 1.0, v83
	v_cvt_pk_u8_f32 v80, v81, 1, v80
	v_fma_f32 v81, v82, s29, -0.5
	v_exp_f32_e32 v82, v76
	v_mov_b32_e32 v76, v77
	v_rcp_f32_e32 v83, v83
	v_mul_f32_e32 v72, 0xbfb8aa3b, v72
	v_mul_f32_e32 v68, 0xbfb8aa3b, v68
	v_mul_f32_e32 v76, 0xbfb8aa3b, v76
	v_exp_f32_e32 v72, v72
	v_mul_f32_e32 v73, 0xbfb8aa3b, v73
	v_exp_f32_e32 v68, v68
	v_mul_f32_e32 v69, 0xbfb8aa3b, v69
	v_exp_f32_e32 v77, v76
	v_mul_f32_e32 v78, 0xbfb8aa3b, v78
	v_exp_f32_e32 v73, v73
	v_mul_f32_e32 v74, 0xbfb8aa3b, v74
	v_exp_f32_e32 v69, v69
	v_mul_f32_e32 v70, 0xbfb8aa3b, v70
	v_exp_f32_e32 v78, v78
	v_mul_f32_e32 v79, 0xbfb8aa3b, v79
	v_exp_f32_e32 v74, v74
	v_mul_f32_e32 v75, 0xbfb8aa3b, v75
	v_exp_f32_e32 v70, v70
	v_mul_f32_e32 v71, 0xbfb8aa3b, v71
	v_cvt_pk_u8_f32 v80, v81, 2, v80
	v_fma_f32 v81, v83, s29, -0.5
	v_exp_f32_e32 v79, v79
	v_exp_f32_e32 v75, v75
	v_exp_f32_e32 v71, v71
	v_cvt_pk_u8_f32 v76, v81, 3, v80
	v_add_f32_e32 v80, 1.0, v82
	v_add_f32_e32 v72, 1.0, v72
	v_add_f32_e32 v68, 1.0, v68
	v_rcp_f32_e32 v80, v80
	v_add_f32_e32 v77, 1.0, v77
	v_rcp_f32_e32 v72, v72
	v_add_f32_e32 v73, 1.0, v73
	v_rcp_f32_e32 v68, v68
	v_add_f32_e32 v69, 1.0, v69
	v_rcp_f32_e32 v77, v77
	v_add_f32_e32 v78, 1.0, v78
	v_rcp_f32_e32 v73, v73
	v_add_f32_e32 v74, 1.0, v74
	v_rcp_f32_e32 v69, v69
	v_add_f32_e32 v70, 1.0, v70
	v_rcp_f32_e32 v78, v78
	v_add_f32_e32 v79, 1.0, v79
	v_rcp_f32_e32 v74, v74
	v_add_f32_e32 v75, 1.0, v75
	v_rcp_f32_e32 v70, v70
	v_add_f32_e32 v71, 1.0, v71
	v_rcp_f32_e32 v79, v79
	v_rcp_f32_e32 v75, v75
	v_rcp_f32_e32 v71, v71
	v_fma_f32 v80, v80, s29, -0.5
	v_fma_f32 v72, v72, s29, -0.5
	v_fma_f32 v68, v68, s29, -0.5
	v_cvt_pk_u8_f32 v80, v80, 0, 0
	v_fma_f32 v77, v77, s29, -0.5
	v_cvt_pk_u8_f32 v72, v72, 0, 0
	v_fma_f32 v73, v73, s29, -0.5
	v_cvt_pk_u8_f32 v68, v68, 0, 0
	v_fma_f32 v69, v69, s29, -0.5
	v_cvt_pk_u8_f32 v77, v77, 1, v80
	v_fma_f32 v78, v78, s29, -0.5
	v_cvt_pk_u8_f32 v72, v73, 1, v72
	v_fma_f32 v73, v74, s29, -0.5
	v_cvt_pk_u8_f32 v68, v69, 1, v68
	v_fma_f32 v69, v70, s29, -0.5
	v_cvt_pk_u8_f32 v77, v78, 2, v77
	v_fma_f32 v78, v79, s29, -0.5
	v_cvt_pk_u8_f32 v72, v73, 2, v72
	v_fma_f32 v73, v75, s29, -0.5
	v_cvt_pk_u8_f32 v68, v69, 2, v68
	v_fma_f32 v69, v71, s29, -0.5
	v_cvt_pk_u8_f32 v77, v78, 3, v77
	v_cvt_pk_u8_f32 v78, v73, 3, v72
	v_cvt_pk_u8_f32 v79, v69, 3, v68
	v_mad_u64_u32 v[68:69], s[4:5], v222, s20, v[2:3]
	global_store_dwordx4 v68, v[76:79], s[72:73] nt
	v_mul_f32_e32 v64, 0xbfb8aa3b, v64
	v_exp_f32_e32 v64, v64
	v_mul_f32_e32 v65, 0xbfb8aa3b, v65
	v_exp_f32_e32 v65, v65
	v_mul_f32_e32 v66, 0xbfb8aa3b, v66
	v_exp_f32_e32 v66, v66
	v_add_f32_e32 v64, 1.0, v64
	v_rcp_f32_e32 v64, v64
	v_add_f32_e32 v65, 1.0, v65
	v_mul_f32_e32 v67, 0xbfb8aa3b, v67
	v_rcp_f32_e32 v65, v65
	v_add_f32_e32 v66, 1.0, v66
	v_exp_f32_e32 v67, v67
	v_rcp_f32_e32 v66, v66
	v_fma_f32 v64, v64, s29, -0.5
	v_cvt_pk_u8_f32 v64, v64, 0, 0
	v_fma_f32 v65, v65, s29, -0.5
	v_mul_f32_e32 v60, 0xbfb8aa3b, v60
	v_add_f32_e32 v67, 1.0, v67
	v_cvt_pk_u8_f32 v64, v65, 1, v64
	v_fma_f32 v65, v66, s29, -0.5
	v_exp_f32_e32 v66, v60
	v_mov_b32_e32 v60, v61
	v_rcp_f32_e32 v67, v67
	v_mul_f32_e32 v56, 0xbfb8aa3b, v56
	v_mul_f32_e32 v52, 0xbfb8aa3b, v52
	v_mul_f32_e32 v60, 0xbfb8aa3b, v60
	v_exp_f32_e32 v56, v56
	v_mul_f32_e32 v57, 0xbfb8aa3b, v57
	v_exp_f32_e32 v52, v52
	v_mul_f32_e32 v53, 0xbfb8aa3b, v53
	v_exp_f32_e32 v61, v60
	v_mul_f32_e32 v62, 0xbfb8aa3b, v62
	v_exp_f32_e32 v57, v57
	v_mul_f32_e32 v58, 0xbfb8aa3b, v58
	v_exp_f32_e32 v53, v53
	v_mul_f32_e32 v54, 0xbfb8aa3b, v54
	v_exp_f32_e32 v62, v62
	v_mul_f32_e32 v63, 0xbfb8aa3b, v63
	v_exp_f32_e32 v58, v58
	v_mul_f32_e32 v59, 0xbfb8aa3b, v59
	v_exp_f32_e32 v54, v54
	v_mul_f32_e32 v55, 0xbfb8aa3b, v55
	v_cvt_pk_u8_f32 v64, v65, 2, v64
	v_fma_f32 v65, v67, s29, -0.5
	v_exp_f32_e32 v63, v63
	v_exp_f32_e32 v59, v59
	v_exp_f32_e32 v55, v55
	v_cvt_pk_u8_f32 v60, v65, 3, v64
	v_add_f32_e32 v64, 1.0, v66
	v_add_f32_e32 v56, 1.0, v56
	v_add_f32_e32 v52, 1.0, v52
	v_rcp_f32_e32 v64, v64
	v_add_f32_e32 v61, 1.0, v61
	v_rcp_f32_e32 v56, v56
	v_add_f32_e32 v57, 1.0, v57
	v_rcp_f32_e32 v52, v52
	v_add_f32_e32 v53, 1.0, v53
	v_rcp_f32_e32 v61, v61
	v_add_f32_e32 v62, 1.0, v62
	v_rcp_f32_e32 v57, v57
	v_add_f32_e32 v58, 1.0, v58
	v_rcp_f32_e32 v53, v53
	v_add_f32_e32 v54, 1.0, v54
	v_rcp_f32_e32 v62, v62
	v_add_f32_e32 v63, 1.0, v63
	v_rcp_f32_e32 v58, v58
	v_add_f32_e32 v59, 1.0, v59
	v_rcp_f32_e32 v54, v54
	v_add_f32_e32 v55, 1.0, v55
	v_rcp_f32_e32 v63, v63
	v_rcp_f32_e32 v59, v59
	v_rcp_f32_e32 v55, v55
	v_fma_f32 v64, v64, s29, -0.5
	v_fma_f32 v56, v56, s29, -0.5
	v_fma_f32 v52, v52, s29, -0.5
	v_cvt_pk_u8_f32 v64, v64, 0, 0
	v_fma_f32 v61, v61, s29, -0.5
	v_cvt_pk_u8_f32 v56, v56, 0, 0
	v_fma_f32 v57, v57, s29, -0.5
	v_cvt_pk_u8_f32 v52, v52, 0, 0
	v_fma_f32 v53, v53, s29, -0.5
	v_cvt_pk_u8_f32 v61, v61, 1, v64
	v_fma_f32 v62, v62, s29, -0.5
	v_cvt_pk_u8_f32 v56, v57, 1, v56
	v_fma_f32 v57, v58, s29, -0.5
	v_cvt_pk_u8_f32 v52, v53, 1, v52
	v_fma_f32 v53, v54, s29, -0.5
	v_cvt_pk_u8_f32 v61, v62, 2, v61
	v_fma_f32 v62, v63, s29, -0.5
	v_cvt_pk_u8_f32 v56, v57, 2, v56
	v_fma_f32 v57, v59, s29, -0.5
	v_cvt_pk_u8_f32 v52, v53, 2, v52
	v_fma_f32 v53, v55, s29, -0.5
	v_cvt_pk_u8_f32 v61, v62, 3, v61
	v_cvt_pk_u8_f32 v62, v57, 3, v56
	v_cvt_pk_u8_f32 v63, v53, 3, v52
	v_mad_u64_u32 v[52:53], s[4:5], v221, s20, v[2:3]
	global_store_dwordx4 v52, v[60:63], s[72:73] nt
	v_mul_f32_e32 v48, 0xbfb8aa3b, v48
	v_exp_f32_e32 v48, v48
	v_mul_f32_e32 v49, 0xbfb8aa3b, v49
	v_exp_f32_e32 v49, v49
	v_mul_f32_e32 v50, 0xbfb8aa3b, v50
	v_exp_f32_e32 v50, v50
	v_add_f32_e32 v48, 1.0, v48
	v_rcp_f32_e32 v48, v48
	v_add_f32_e32 v49, 1.0, v49
	v_mul_f32_e32 v51, 0xbfb8aa3b, v51
	v_rcp_f32_e32 v49, v49
	v_add_f32_e32 v50, 1.0, v50
	v_exp_f32_e32 v51, v51
	v_rcp_f32_e32 v50, v50
	v_fma_f32 v48, v48, s29, -0.5
	v_cvt_pk_u8_f32 v48, v48, 0, 0
	v_fma_f32 v49, v49, s29, -0.5
	v_mul_f32_e32 v44, 0xbfb8aa3b, v44
	v_add_f32_e32 v51, 1.0, v51
	v_cvt_pk_u8_f32 v48, v49, 1, v48
	v_fma_f32 v49, v50, s29, -0.5
	v_exp_f32_e32 v50, v44
	v_mov_b32_e32 v44, v45
	v_rcp_f32_e32 v51, v51
	v_mul_f32_e32 v40, 0xbfb8aa3b, v40
	v_mul_f32_e32 v36, 0xbfb8aa3b, v36
	v_mul_f32_e32 v44, 0xbfb8aa3b, v44
	v_exp_f32_e32 v40, v40
	v_mul_f32_e32 v41, 0xbfb8aa3b, v41
	v_exp_f32_e32 v36, v36
	v_mul_f32_e32 v37, 0xbfb8aa3b, v37
	v_exp_f32_e32 v45, v44
	v_mul_f32_e32 v46, 0xbfb8aa3b, v46
	v_exp_f32_e32 v41, v41
	v_mul_f32_e32 v42, 0xbfb8aa3b, v42
	v_exp_f32_e32 v37, v37
	v_mul_f32_e32 v38, 0xbfb8aa3b, v38
	v_exp_f32_e32 v46, v46
	v_mul_f32_e32 v47, 0xbfb8aa3b, v47
	v_exp_f32_e32 v42, v42
	v_mul_f32_e32 v43, 0xbfb8aa3b, v43
	v_exp_f32_e32 v38, v38
	v_mul_f32_e32 v39, 0xbfb8aa3b, v39
	v_cvt_pk_u8_f32 v48, v49, 2, v48
	v_fma_f32 v49, v51, s29, -0.5
	v_exp_f32_e32 v47, v47
	v_exp_f32_e32 v43, v43
	v_exp_f32_e32 v39, v39
	v_cvt_pk_u8_f32 v44, v49, 3, v48
	v_add_f32_e32 v48, 1.0, v50
	v_add_f32_e32 v40, 1.0, v40
	v_add_f32_e32 v36, 1.0, v36
	v_rcp_f32_e32 v48, v48
	v_add_f32_e32 v45, 1.0, v45
	v_rcp_f32_e32 v40, v40
	v_add_f32_e32 v41, 1.0, v41
	v_rcp_f32_e32 v36, v36
	v_add_f32_e32 v37, 1.0, v37
	v_rcp_f32_e32 v45, v45
	v_add_f32_e32 v46, 1.0, v46
	v_rcp_f32_e32 v41, v41
	v_add_f32_e32 v42, 1.0, v42
	v_rcp_f32_e32 v37, v37
	v_add_f32_e32 v38, 1.0, v38
	v_rcp_f32_e32 v46, v46
	v_add_f32_e32 v47, 1.0, v47
	v_rcp_f32_e32 v42, v42
	v_add_f32_e32 v43, 1.0, v43
	v_rcp_f32_e32 v38, v38
	v_add_f32_e32 v39, 1.0, v39
	v_rcp_f32_e32 v47, v47
	v_rcp_f32_e32 v43, v43
	v_rcp_f32_e32 v39, v39
	v_fma_f32 v48, v48, s29, -0.5
	v_fma_f32 v40, v40, s29, -0.5
	v_fma_f32 v36, v36, s29, -0.5
	v_cvt_pk_u8_f32 v48, v48, 0, 0
	v_fma_f32 v45, v45, s29, -0.5
	v_cvt_pk_u8_f32 v40, v40, 0, 0
	v_fma_f32 v41, v41, s29, -0.5
	v_cvt_pk_u8_f32 v36, v36, 0, 0
	v_fma_f32 v37, v37, s29, -0.5
	v_cvt_pk_u8_f32 v45, v45, 1, v48
	v_fma_f32 v46, v46, s29, -0.5
	v_cvt_pk_u8_f32 v40, v41, 1, v40
	v_fma_f32 v41, v42, s29, -0.5
	v_cvt_pk_u8_f32 v36, v37, 1, v36
	v_fma_f32 v37, v38, s29, -0.5
	v_cvt_pk_u8_f32 v45, v46, 2, v45
	v_fma_f32 v46, v47, s29, -0.5
	v_cvt_pk_u8_f32 v40, v41, 2, v40
	v_fma_f32 v41, v43, s29, -0.5
	v_cvt_pk_u8_f32 v36, v37, 2, v36
	v_fma_f32 v37, v39, s29, -0.5
	v_cvt_pk_u8_f32 v45, v46, 3, v45
	v_cvt_pk_u8_f32 v46, v41, 3, v40
	v_cvt_pk_u8_f32 v47, v37, 3, v36
	v_mad_u64_u32 v[36:37], s[4:5], v220, s20, v[2:3]
	global_store_dwordx4 v36, v[44:47], s[72:73] nt
	v_mul_f32_e32 v32, 0xbfb8aa3b, v32
	v_exp_f32_e32 v32, v32
	v_mul_f32_e32 v33, 0xbfb8aa3b, v33
	v_exp_f32_e32 v33, v33
	v_mul_f32_e32 v34, 0xbfb8aa3b, v34
	v_exp_f32_e32 v34, v34
	v_add_f32_e32 v32, 1.0, v32
	v_rcp_f32_e32 v32, v32
	v_add_f32_e32 v33, 1.0, v33
	v_mul_f32_e32 v35, 0xbfb8aa3b, v35
	v_rcp_f32_e32 v33, v33
	v_add_f32_e32 v34, 1.0, v34
	v_exp_f32_e32 v35, v35
	v_rcp_f32_e32 v34, v34
	v_fma_f32 v32, v32, s29, -0.5
	v_cvt_pk_u8_f32 v32, v32, 0, 0
	v_fma_f32 v33, v33, s29, -0.5
	v_mul_f32_e32 v28, 0xbfb8aa3b, v28
	v_add_f32_e32 v35, 1.0, v35
	v_cvt_pk_u8_f32 v32, v33, 1, v32
	v_fma_f32 v33, v34, s29, -0.5
	v_exp_f32_e32 v34, v28
	v_mov_b32_e32 v28, v29
	v_rcp_f32_e32 v35, v35
	v_mul_f32_e32 v24, 0xbfb8aa3b, v24
	v_mul_f32_e32 v20, 0xbfb8aa3b, v20
	v_mul_f32_e32 v28, 0xbfb8aa3b, v28
	v_exp_f32_e32 v24, v24
	v_mul_f32_e32 v25, 0xbfb8aa3b, v25
	v_exp_f32_e32 v20, v20
	v_mul_f32_e32 v21, 0xbfb8aa3b, v21
	v_exp_f32_e32 v29, v28
	v_mul_f32_e32 v30, 0xbfb8aa3b, v30
	v_exp_f32_e32 v25, v25
	v_mul_f32_e32 v26, 0xbfb8aa3b, v26
	v_exp_f32_e32 v21, v21
	v_mul_f32_e32 v22, 0xbfb8aa3b, v22
	v_exp_f32_e32 v30, v30
	v_mul_f32_e32 v31, 0xbfb8aa3b, v31
	v_exp_f32_e32 v26, v26
	v_mul_f32_e32 v27, 0xbfb8aa3b, v27
	v_exp_f32_e32 v22, v22
	v_mul_f32_e32 v23, 0xbfb8aa3b, v23
	v_cvt_pk_u8_f32 v32, v33, 2, v32
	v_fma_f32 v33, v35, s29, -0.5
	v_exp_f32_e32 v31, v31
	v_exp_f32_e32 v27, v27
	v_exp_f32_e32 v23, v23
	v_cvt_pk_u8_f32 v28, v33, 3, v32
	v_add_f32_e32 v32, 1.0, v34
	v_add_f32_e32 v24, 1.0, v24
	v_add_f32_e32 v20, 1.0, v20
	v_rcp_f32_e32 v32, v32
	v_add_f32_e32 v29, 1.0, v29
	v_rcp_f32_e32 v24, v24
	v_add_f32_e32 v25, 1.0, v25
	v_rcp_f32_e32 v20, v20
	v_add_f32_e32 v21, 1.0, v21
	v_rcp_f32_e32 v29, v29
	v_add_f32_e32 v30, 1.0, v30
	v_rcp_f32_e32 v25, v25
	v_add_f32_e32 v26, 1.0, v26
	v_rcp_f32_e32 v21, v21
	v_add_f32_e32 v22, 1.0, v22
	v_rcp_f32_e32 v30, v30
	v_add_f32_e32 v31, 1.0, v31
	v_rcp_f32_e32 v26, v26
	v_add_f32_e32 v27, 1.0, v27
	v_rcp_f32_e32 v22, v22
	v_add_f32_e32 v23, 1.0, v23
	v_rcp_f32_e32 v31, v31
	v_rcp_f32_e32 v27, v27
	v_rcp_f32_e32 v23, v23
	v_fma_f32 v32, v32, s29, -0.5
	v_fma_f32 v24, v24, s29, -0.5
	v_fma_f32 v20, v20, s29, -0.5
	v_cvt_pk_u8_f32 v32, v32, 0, 0
	v_fma_f32 v29, v29, s29, -0.5
	v_cvt_pk_u8_f32 v24, v24, 0, 0
	v_fma_f32 v25, v25, s29, -0.5
	v_cvt_pk_u8_f32 v20, v20, 0, 0
	v_fma_f32 v21, v21, s29, -0.5
	v_cvt_pk_u8_f32 v29, v29, 1, v32
	v_fma_f32 v30, v30, s29, -0.5
	v_cvt_pk_u8_f32 v24, v25, 1, v24
	v_fma_f32 v25, v26, s29, -0.5
	v_cvt_pk_u8_f32 v20, v21, 1, v20
	v_fma_f32 v21, v22, s29, -0.5
	v_cvt_pk_u8_f32 v29, v30, 2, v29
	v_fma_f32 v30, v31, s29, -0.5
	v_cvt_pk_u8_f32 v24, v25, 2, v24
	v_fma_f32 v25, v27, s29, -0.5
	v_cvt_pk_u8_f32 v20, v21, 2, v20
	v_fma_f32 v21, v23, s29, -0.5
	v_cvt_pk_u8_f32 v29, v30, 3, v29
	v_cvt_pk_u8_f32 v30, v25, 3, v24
	v_cvt_pk_u8_f32 v31, v21, 3, v20
	v_mad_u64_u32 v[20:21], s[4:5], v195, s20, v[2:3]
	global_store_dwordx4 v20, v[28:31], s[72:73] nt
	v_mul_f32_e32 v16, 0xbfb8aa3b, v16
	v_exp_f32_e32 v16, v16
	v_mul_f32_e32 v17, 0xbfb8aa3b, v17
	v_exp_f32_e32 v17, v17
	v_mul_f32_e32 v18, 0xbfb8aa3b, v18
	v_exp_f32_e32 v18, v18
	v_add_f32_e32 v16, 1.0, v16
	v_rcp_f32_e32 v16, v16
	v_add_f32_e32 v17, 1.0, v17
	v_mul_f32_e32 v19, 0xbfb8aa3b, v19
	v_rcp_f32_e32 v17, v17
	v_add_f32_e32 v18, 1.0, v18
	v_exp_f32_e32 v19, v19
	v_rcp_f32_e32 v18, v18
	v_fma_f32 v16, v16, s29, -0.5
	v_cvt_pk_u8_f32 v16, v16, 0, 0
	v_fma_f32 v17, v17, s29, -0.5
	v_mul_f32_e32 v12, 0xbfb8aa3b, v12
	v_add_f32_e32 v19, 1.0, v19
	v_cvt_pk_u8_f32 v16, v17, 1, v16
	v_fma_f32 v17, v18, s29, -0.5
	v_exp_f32_e32 v18, v12
	v_mov_b32_e32 v12, v13
	v_rcp_f32_e32 v19, v19
	v_mul_f32_e32 v8, 0xbfb8aa3b, v8
	v_mul_f32_e32 v4, 0xbfb8aa3b, v4
	v_mul_f32_e32 v12, 0xbfb8aa3b, v12
	v_exp_f32_e32 v8, v8
	v_mul_f32_e32 v9, 0xbfb8aa3b, v9
	v_exp_f32_e32 v4, v4
	v_mul_f32_e32 v5, 0xbfb8aa3b, v5
	v_exp_f32_e32 v13, v12
	v_mul_f32_e32 v14, 0xbfb8aa3b, v14
	v_exp_f32_e32 v9, v9
	v_mul_f32_e32 v10, 0xbfb8aa3b, v10
	v_exp_f32_e32 v5, v5
	v_mul_f32_e32 v6, 0xbfb8aa3b, v6
	v_exp_f32_e32 v14, v14
	v_mul_f32_e32 v15, 0xbfb8aa3b, v15
	v_exp_f32_e32 v10, v10
	v_mul_f32_e32 v11, 0xbfb8aa3b, v11
	v_exp_f32_e32 v6, v6
	v_mul_f32_e32 v7, 0xbfb8aa3b, v7
	v_cvt_pk_u8_f32 v16, v17, 2, v16
	v_fma_f32 v17, v19, s29, -0.5
	v_exp_f32_e32 v15, v15
	v_exp_f32_e32 v11, v11
	v_exp_f32_e32 v7, v7
	v_cvt_pk_u8_f32 v12, v17, 3, v16
	v_add_f32_e32 v16, 1.0, v18
	v_add_f32_e32 v8, 1.0, v8
	v_add_f32_e32 v4, 1.0, v4
	v_rcp_f32_e32 v16, v16
	v_add_f32_e32 v13, 1.0, v13
	v_rcp_f32_e32 v8, v8
	v_add_f32_e32 v9, 1.0, v9
	v_rcp_f32_e32 v4, v4
	v_add_f32_e32 v5, 1.0, v5
	v_rcp_f32_e32 v13, v13
	v_add_f32_e32 v14, 1.0, v14
	v_rcp_f32_e32 v9, v9
	v_add_f32_e32 v10, 1.0, v10
	v_rcp_f32_e32 v5, v5
	v_add_f32_e32 v6, 1.0, v6
	v_rcp_f32_e32 v14, v14
	v_add_f32_e32 v15, 1.0, v15
	v_rcp_f32_e32 v10, v10
	v_add_f32_e32 v11, 1.0, v11
	v_rcp_f32_e32 v6, v6
	v_add_f32_e32 v7, 1.0, v7
	v_rcp_f32_e32 v15, v15
	v_rcp_f32_e32 v11, v11
	v_rcp_f32_e32 v7, v7
	v_fma_f32 v16, v16, s29, -0.5
	v_fma_f32 v8, v8, s29, -0.5
	v_fma_f32 v4, v4, s29, -0.5
	v_cvt_pk_u8_f32 v16, v16, 0, 0
	v_fma_f32 v13, v13, s29, -0.5
	v_cvt_pk_u8_f32 v8, v8, 0, 0
	v_fma_f32 v9, v9, s29, -0.5
	v_cvt_pk_u8_f32 v4, v4, 0, 0
	v_fma_f32 v5, v5, s29, -0.5
	v_cvt_pk_u8_f32 v13, v13, 1, v16
	v_fma_f32 v14, v14, s29, -0.5
	v_cvt_pk_u8_f32 v8, v9, 1, v8
	v_fma_f32 v9, v10, s29, -0.5
	v_cvt_pk_u8_f32 v4, v5, 1, v4
	v_fma_f32 v5, v6, s29, -0.5
	v_cvt_pk_u8_f32 v13, v14, 2, v13
	v_fma_f32 v14, v15, s29, -0.5
	v_cvt_pk_u8_f32 v8, v9, 2, v8
	v_fma_f32 v9, v11, s29, -0.5
	v_cvt_pk_u8_f32 v4, v5, 2, v4
	v_fma_f32 v5, v7, s29, -0.5
	v_cvt_pk_u8_f32 v13, v14, 3, v13
	v_cvt_pk_u8_f32 v14, v9, 3, v8
	v_cvt_pk_u8_f32 v15, v5, 3, v4
	v_mad_u64_u32 v[4:5], s[4:5], v194, s20, v[2:3]
	global_store_dwordx4 v4, v[12:15], s[72:73] nt
	s_andn2_b64 vcc, exec, s[74:75]
	s_mov_b64 s[4:5], -1
	s_cbranch_vccnz .LBB0_1263
	s_branch .LBB0_1539
